# v24 + sample-chain output tail: gain/gate loads issued before the item's write-through state stores, tail waits vmcnt(8) (no longer behind the store acknowledgements)
# baseline (speedup 1.0000x reference)
.LBB0_1192:
	s_and_b32 s4, s7, -4
	s_and_b32 s1, s6, 0x180
	s_waitcnt lgkmcnt(0)
	s_add_i32 s0, s90, s7
	s_add_i32 s2, s4, 0x4000
	s_lshl_b32 s1, s1, 1
	s_mul_i32 s5, s4, 0x1600
	s_add_u32 s8, s52, s1
	s_addc_u32 s9, s53, 0
	s_mul_hi_i32 s3, s2, 0x1600
	s_add_i32 s2, s5, 0x5800000
	s_add_u32 s2, s8, s2
	s_waitcnt vmcnt(9)
	v_lshl_add_u64 v[0:1], v[132:133], 0, v[130:131]
	s_addc_u32 s3, s9, s3
	global_load_dwordx4 v[154:157], v[0:1], off
	global_load_dwordx4 v[168:171], v[0:1], off offset:512
	global_load_dwordx4 v[118:121], v[0:1], off offset:1024
	global_load_dwordx4 v[114:117], v[0:1], off offset:1536
	global_load_dwordx4 v[110:113], v[0:1], off offset:2048
	global_load_dwordx4 v[106:109], v[0:1], off offset:2560
	global_load_dwordx4 v[94:97], v[0:1], off offset:3072
	global_load_dwordx4 v[90:93], v[0:1], off offset:3584
	v_lshl_add_u64 v[0:1], s[2:3], 0, v[136:137]
	global_load_dwordx4 v[98:101], v[0:1], off offset:2560
	global_load_dwordx4 v[102:105], v[0:1], off offset:1536
	global_load_dwordx2 v[152:153], v166, s[2:3] offset:3584
	s_add_i32 s2, s4, 0x4001
	s_mul_hi_i32 s3, s2, 0x1600
	s_add_i32 s2, s5, 0x5801600
	s_add_u32 s2, s8, s2
	s_addc_u32 s3, s9, s3
	v_lshl_add_u64 v[0:1], s[2:3], 0, v[136:137]
	global_load_dwordx4 v[82:85], v[0:1], off offset:2560
	global_load_dwordx4 v[86:89], v[0:1], off offset:1536
	global_load_dwordx2 v[150:151], v166, s[2:3] offset:3584
	s_add_i32 s2, s4, 0x4002
	s_mul_hi_i32 s3, s2, 0x1600
	s_add_i32 s2, s5, 0x5802c00
	s_add_u32 s2, s8, s2
	s_addc_u32 s3, s9, s3
	v_lshl_add_u64 v[0:1], s[2:3], 0, v[136:137]
	global_load_dwordx4 v[74:77], v[0:1], off offset:2560
	global_load_dwordx4 v[78:81], v[0:1], off offset:1536
	global_load_dwordx2 v[148:149], v166, s[2:3] offset:3584
	s_add_i32 s2, s4, 0x4003
	s_add_i32 s5, s5, 0x5804200
	s_mul_hi_i32 s3, s2, 0x1600
	s_add_u32 s2, s8, s5
	s_addc_u32 s3, s9, s3
	v_lshl_add_u64 v[0:1], s[2:3], 0, v[136:137]
	s_cmpk_lt_i32 s0, 0x200
	global_load_dwordx4 v[66:69], v[0:1], off offset:2560
	global_load_dwordx4 v[70:73], v[0:1], off offset:1536
	global_load_dwordx2 v[146:147], v166, s[2:3] offset:3584
	s_cselect_b64 s[2:3], -1, 0
	s_and_b64 s[8:9], s[2:3], exec
	s_cselect_b32 s8, s0, 0x1ff
	s_ashr_i32 s9, s8, 31
	s_lshl_b64 s[10:11], s[8:9], 16
	s_and_b32 s5, s8, -4
	s_lshl_b32 s8, s8, 8
	s_add_i32 s9, s5, 0x4000
	s_and_b32 s8, s8, 0x300
	v_lshl_add_u64 v[0:1], v[122:123], 0, s[10:11]
	s_mul_i32 s10, s5, 0x1600
	s_add_u32 s11, s52, s8
	s_addc_u32 s12, s53, 0
	s_add_i32 s8, s10, 0x5800000
	s_mul_hi_i32 s9, s9, 0x1600
	s_add_u32 s8, s11, s8
	s_addc_u32 s9, s12, s9
	global_load_dwordx4 v[62:65], v[0:1], off
	global_load_dwordx4 v[58:61], v[0:1], off offset:512
	global_load_dwordx4 v[54:57], v[0:1], off offset:1024
	global_load_dwordx4 v[50:53], v[0:1], off offset:1536
	global_load_dwordx4 v[46:49], v[0:1], off offset:2048
	global_load_dwordx4 v[42:45], v[0:1], off offset:2560
	global_load_dwordx4 v[30:33], v[0:1], off offset:3072
	global_load_dwordx4 v[26:29], v[0:1], off offset:3584
	v_lshl_add_u64 v[0:1], s[8:9], 0, v[136:137]
	global_load_dwordx4 v[38:41], v[0:1], off offset:2560
	global_load_dwordx4 v[34:37], v[0:1], off offset:1536
	global_load_dwordx2 v[144:145], v166, s[8:9] offset:3584
	s_add_i32 s8, s5, 0x4001
	s_mul_hi_i32 s9, s8, 0x1600
	s_add_i32 s8, s10, 0x5801600
	s_add_u32 s8, s11, s8
	s_addc_u32 s9, s12, s9
	v_lshl_add_u64 v[0:1], s[8:9], 0, v[136:137]
	global_load_dwordx4 v[22:25], v[0:1], off offset:2560
	global_load_dwordx4 v[18:21], v[0:1], off offset:1536
	global_load_dwordx2 v[142:143], v166, s[8:9] offset:3584
	s_add_i32 s8, s5, 0x4002
	s_mul_hi_i32 s9, s8, 0x1600
	s_add_i32 s8, s10, 0x5802c00
	s_add_u32 s8, s11, s8
	s_addc_u32 s9, s12, s9
	v_lshl_add_u64 v[0:1], s[8:9], 0, v[136:137]
	s_addk_i32 s5, 0x4003
	s_add_i32 s10, s10, 0x5804200
	global_load_dwordx4 v[12:15], v[0:1], off offset:2560
	global_load_dwordx4 v[8:11], v[0:1], off offset:1536
	global_load_dwordx2 v[140:141], v166, s[8:9] offset:3584
	s_mul_hi_i32 s5, s5, 0x1600
	s_add_u32 s8, s11, s10
	s_addc_u32 s9, s12, s5
	v_lshl_add_u64 v[0:1], s[8:9], 0, v[136:137]
	global_load_dwordx4 v[4:7], v[0:1], off offset:2560
	s_nop 0
	global_load_dwordx4 v[0:3], v[0:1], off offset:1536
	s_nop 0
	global_load_dwordx2 v[138:139], v166, s[8:9] offset:3584
	v_readfirstlane_b32 s5, v17
	s_ashr_i32 s5, s5, 6
	s_cmp_gt_i32 s5, 3
	s_waitcnt vmcnt(30)
	v_lshlrev_b32_e32 v158, 16, v102
	s_waitcnt vmcnt(29)
	v_lshlrev_b32_e32 v160, 16, v152
	v_and_b32_e32 v161, 0xffff0000, v152
	v_lshlrev_b32_e32 v152, 16, v98
	v_exp_f32_e32 v172, v152
	v_lshlrev_b32_e32 v162, 16, v153
	v_and_b32_e32 v163, 0xffff0000, v153
	v_sub_f32_e32 v152, 1.0, v172
	v_pk_mul_f32 v[174:175], v[152:153], v[160:161] op_sel_hi:[0,1]
	v_pk_mul_f32 v[152:153], v[152:153], v[162:163] op_sel_hi:[0,1]
	v_pk_fma_f32 v[152:153], v[156:157], v[172:173], v[152:153] op_sel_hi:[1,0,1]
	v_and_b32_e32 v156, 0xffff0000, v98
	v_and_b32_e32 v98, 0xffff0000, v102
	v_exp_f32_e32 v102, v156
	v_pk_fma_f32 v[154:155], v[154:155], v[172:173], v[174:175] op_sel_hi:[1,0,1]
	v_pk_fma_f32 v[174:175], v[158:159], v[152:153], 0 op_sel_hi:[0,1,0]
	v_pk_fma_f32 v[172:173], v[158:159], v[154:155], 0 op_sel_hi:[0,1,0]
	v_sub_f32_e32 v156, 1.0, v102
	v_pk_mul_f32 v[158:159], v[156:157], v[162:163] op_sel_hi:[0,1]
	v_pk_mul_f32 v[156:157], v[156:157], v[160:161] op_sel_hi:[0,1]
	v_pk_fma_f32 v[156:157], v[168:169], v[102:103], v[156:157] op_sel_hi:[1,0,1]
	v_pk_fma_f32 v[158:159], v[170:171], v[102:103], v[158:159] op_sel_hi:[1,0,1]
	v_lshlrev_b32_e32 v102, 16, v99
	v_exp_f32_e32 v102, v102
	v_pk_fma_f32 v[170:171], v[98:99], v[156:157], v[172:173] op_sel_hi:[0,1,1]
	v_pk_fma_f32 v[168:169], v[98:99], v[158:159], v[174:175] op_sel_hi:[0,1,1]
	v_lshlrev_b32_e32 v98, 16, v103
	v_sub_f32_e32 v172, 1.0, v102
	v_pk_mul_f32 v[174:175], v[172:173], v[160:161] op_sel_hi:[0,1]
	v_pk_mul_f32 v[172:173], v[172:173], v[162:163] op_sel_hi:[0,1]
	v_pk_fma_f32 v[120:121], v[120:121], v[102:103], v[172:173] op_sel_hi:[1,0,1]
	v_pk_fma_f32 v[118:119], v[118:119], v[102:103], v[174:175] op_sel_hi:[1,0,1]
	v_pk_fma_f32 v[168:169], v[98:99], v[120:121], v[168:169] op_sel_hi:[0,1,1]
	v_pk_fma_f32 v[170:171], v[98:99], v[118:119], v[170:171] op_sel_hi:[0,1,1]
	v_and_b32_e32 v98, 0xffff0000, v99
	v_exp_f32_e32 v102, v98
	v_and_b32_e32 v172, 0xffff0000, v103
	v_sub_f32_e32 v98, 1.0, v102
	v_pk_mul_f32 v[174:175], v[98:99], v[162:163] op_sel_hi:[0,1]
	v_pk_mul_f32 v[98:99], v[98:99], v[160:161] op_sel_hi:[0,1]
	v_pk_fma_f32 v[98:99], v[114:115], v[102:103], v[98:99] op_sel_hi:[1,0,1]
	v_pk_fma_f32 v[102:103], v[116:117], v[102:103], v[174:175] op_sel_hi:[1,0,1]
	v_pk_fma_f32 v[116:117], v[172:173], v[98:99], v[170:171] op_sel_hi:[0,1,1]
	v_pk_fma_f32 v[114:115], v[172:173], v[102:103], v[168:169] op_sel_hi:[0,1,1]
	v_lshlrev_b32_e32 v169, 16, v100
	v_exp_f32_e32 v170, v169
	v_lshlrev_b32_e32 v168, 16, v104
	v_sub_f32_e32 v172, 1.0, v170
	v_pk_mul_f32 v[174:175], v[172:173], v[160:161] op_sel_hi:[0,1]
	v_pk_mul_f32 v[172:173], v[172:173], v[162:163] op_sel_hi:[0,1]
	v_pk_fma_f32 v[112:113], v[112:113], v[170:171], v[172:173] op_sel_hi:[1,0,1]
	v_pk_fma_f32 v[110:111], v[110:111], v[170:171], v[174:175] op_sel_hi:[1,0,1]
	v_pk_fma_f32 v[114:115], v[168:169], v[112:113], v[114:115] op_sel_hi:[0,1,1]
	v_pk_fma_f32 v[116:117], v[168:169], v[110:111], v[116:117] op_sel_hi:[0,1,1]
	v_and_b32_e32 v168, 0xffff0000, v100
	v_and_b32_e32 v100, 0xffff0000, v104
	v_exp_f32_e32 v104, v168
	s_nop 0
	v_sub_f32_e32 v168, 1.0, v104
	v_pk_mul_f32 v[170:171], v[168:169], v[162:163] op_sel_hi:[0,1]
	v_pk_mul_f32 v[168:169], v[168:169], v[160:161] op_sel_hi:[0,1]
	v_pk_fma_f32 v[106:107], v[106:107], v[104:105], v[168:169] op_sel_hi:[1,0,1]
	v_pk_fma_f32 v[108:109], v[108:109], v[104:105], v[170:171] op_sel_hi:[1,0,1]
	v_lshlrev_b32_e32 v104, 16, v101
	v_exp_f32_e32 v104, v104
	v_pk_fma_f32 v[114:115], v[100:101], v[108:109], v[114:115] op_sel_hi:[0,1,1]
	v_pk_fma_f32 v[116:117], v[100:101], v[106:107], v[116:117] op_sel_hi:[0,1,1]
	v_lshlrev_b32_e32 v100, 16, v105
	v_sub_f32_e32 v168, 1.0, v104
	v_pk_mul_f32 v[170:171], v[168:169], v[160:161] op_sel_hi:[0,1]
	v_pk_mul_f32 v[168:169], v[168:169], v[162:163] op_sel_hi:[0,1]
	v_pk_fma_f32 v[96:97], v[96:97], v[104:105], v[168:169] op_sel_hi:[1,0,1]
	v_pk_fma_f32 v[94:95], v[94:95], v[104:105], v[170:171] op_sel_hi:[1,0,1]
	v_pk_fma_f32 v[114:115], v[100:101], v[96:97], v[114:115] op_sel_hi:[0,1,1]
	v_pk_fma_f32 v[168:169], v[100:101], v[94:95], v[116:117] op_sel_hi:[0,1,1]
	v_and_b32_e32 v101, 0xffff0000, v101
	v_exp_f32_e32 v104, v101
	v_and_b32_e32 v100, 0xffff0000, v105
	v_sub_f32_e32 v116, 1.0, v104
	v_pk_mul_f32 v[162:163], v[116:117], v[162:163] op_sel_hi:[0,1]
	v_pk_mul_f32 v[116:117], v[116:117], v[160:161] op_sel_hi:[0,1]
	v_pk_fma_f32 v[90:91], v[90:91], v[104:105], v[116:117] op_sel_hi:[1,0,1]
	v_pk_fma_f32 v[92:93], v[92:93], v[104:105], v[162:163] op_sel_hi:[1,0,1]
	s_waitcnt vmcnt(26)
	v_lshlrev_b32_e32 v160, 16, v150
	v_pk_fma_f32 v[116:117], v[100:101], v[92:93], v[114:115] op_sel_hi:[0,1,1]
	v_pk_fma_f32 v[114:115], v[100:101], v[90:91], v[168:169] op_sel_hi:[0,1,1]
	v_lshlrev_b32_e32 v100, 16, v82
	v_exp_f32_e32 v104, v100
	v_and_b32_e32 v161, 0xffff0000, v150
	v_lshlrev_b32_e32 v150, 16, v151
	v_and_b32_e32 v151, 0xffff0000, v151
	v_sub_f32_e32 v100, 1.0, v104
	ds_write_b128 v127, v[114:117]
	v_pk_mul_f32 v[116:117], v[100:101], v[160:161] op_sel_hi:[0,1]
	v_pk_mul_f32 v[100:101], v[100:101], v[150:151] op_sel_hi:[0,1]
	v_lshlrev_b32_e32 v114, 16, v86
	v_pk_fma_f32 v[100:101], v[104:105], v[152:153], v[100:101] op_sel_hi:[0,1,1]
	v_pk_fma_f32 v[104:105], v[104:105], v[154:155], v[116:117] op_sel_hi:[0,1,1]
	v_pk_fma_f32 v[152:153], v[114:115], v[104:105], 0 op_sel_hi:[0,1,0]
	v_pk_fma_f32 v[154:155], v[114:115], v[100:101], 0 op_sel_hi:[0,1,0]
	v_and_b32_e32 v114, 0xffff0000, v82
	v_and_b32_e32 v82, 0xffff0000, v86
	v_exp_f32_e32 v86, v114
	s_nop 0
	v_sub_f32_e32 v114, 1.0, v86
	v_pk_mul_f32 v[116:117], v[114:115], v[150:151] op_sel_hi:[0,1]
	v_pk_mul_f32 v[114:115], v[114:115], v[160:161] op_sel_hi:[0,1]
	v_pk_fma_f32 v[114:115], v[86:87], v[156:157], v[114:115] op_sel_hi:[0,1,1]
	v_pk_fma_f32 v[116:117], v[86:87], v[158:159], v[116:117] op_sel_hi:[0,1,1]
	v_lshlrev_b32_e32 v86, 16, v83
	v_exp_f32_e32 v86, v86
	v_pk_fma_f32 v[154:155], v[82:83], v[116:117], v[154:155] op_sel_hi:[0,1,1]
	v_pk_fma_f32 v[152:153], v[82:83], v[114:115], v[152:153] op_sel_hi:[0,1,1]
	v_lshlrev_b32_e32 v82, 16, v87
	v_sub_f32_e32 v156, 1.0, v86
	v_pk_mul_f32 v[158:159], v[156:157], v[160:161] op_sel_hi:[0,1]
	v_pk_mul_f32 v[156:157], v[156:157], v[150:151] op_sel_hi:[0,1]
	v_pk_fma_f32 v[120:121], v[86:87], v[120:121], v[156:157] op_sel_hi:[0,1,1]
	v_pk_fma_f32 v[118:119], v[86:87], v[118:119], v[158:159] op_sel_hi:[0,1,1]
	v_pk_fma_f32 v[152:153], v[82:83], v[118:119], v[152:153] op_sel_hi:[0,1,1]
	v_pk_fma_f32 v[154:155], v[82:83], v[120:121], v[154:155] op_sel_hi:[0,1,1]
	v_and_b32_e32 v83, 0xffff0000, v83
	v_exp_f32_e32 v156, v83
	v_and_b32_e32 v82, 0xffff0000, v87
	v_sub_f32_e32 v86, 1.0, v156
	v_pk_mul_f32 v[158:159], v[86:87], v[150:151] op_sel_hi:[0,1]
	v_pk_mul_f32 v[86:87], v[86:87], v[160:161] op_sel_hi:[0,1]
	v_pk_fma_f32 v[86:87], v[156:157], v[98:99], v[86:87] op_sel_hi:[0,1,1]
	v_pk_fma_f32 v[98:99], v[156:157], v[102:103], v[158:159] op_sel_hi:[0,1,1]
	v_lshlrev_b32_e32 v102, 16, v84
	v_exp_f32_e32 v156, v102
	v_pk_fma_f32 v[154:155], v[82:83], v[98:99], v[154:155] op_sel_hi:[0,1,1]
	v_pk_fma_f32 v[82:83], v[82:83], v[86:87], v[152:153] op_sel_hi:[0,1,1]
	v_lshlrev_b32_e32 v152, 16, v88
	v_sub_f32_e32 v102, 1.0, v156
	v_pk_mul_f32 v[158:159], v[102:103], v[160:161] op_sel_hi:[0,1]
	v_pk_mul_f32 v[102:103], v[102:103], v[150:151] op_sel_hi:[0,1]
	v_pk_fma_f32 v[102:103], v[156:157], v[112:113], v[102:103] op_sel_hi:[0,1,1]
	v_pk_fma_f32 v[110:111], v[156:157], v[110:111], v[158:159] op_sel_hi:[0,1,1]
	v_pk_fma_f32 v[82:83], v[152:153], v[110:111], v[82:83] op_sel_hi:[0,1,1]
	v_pk_fma_f32 v[112:113], v[152:153], v[102:103], v[154:155] op_sel_hi:[0,1,1]
	v_and_b32_e32 v152, 0xffff0000, v84
	v_and_b32_e32 v84, 0xffff0000, v88
	v_exp_f32_e32 v88, v152
	s_nop 0
	v_sub_f32_e32 v152, 1.0, v88
	v_pk_mul_f32 v[154:155], v[152:153], v[150:151] op_sel_hi:[0,1]
	v_pk_mul_f32 v[152:153], v[152:153], v[160:161] op_sel_hi:[0,1]
	v_pk_fma_f32 v[106:107], v[88:89], v[106:107], v[152:153] op_sel_hi:[0,1,1]
	v_pk_fma_f32 v[108:109], v[88:89], v[108:109], v[154:155] op_sel_hi:[0,1,1]
	v_lshlrev_b32_e32 v88, 16, v85
	v_exp_f32_e32 v88, v88
	v_pk_fma_f32 v[112:113], v[84:85], v[108:109], v[112:113] op_sel_hi:[0,1,1]
	v_pk_fma_f32 v[82:83], v[84:85], v[106:107], v[82:83] op_sel_hi:[0,1,1]
	v_lshlrev_b32_e32 v84, 16, v89
	v_sub_f32_e32 v152, 1.0, v88
	v_pk_mul_f32 v[154:155], v[152:153], v[160:161] op_sel_hi:[0,1]
	v_pk_mul_f32 v[152:153], v[152:153], v[150:151] op_sel_hi:[0,1]
	v_pk_fma_f32 v[96:97], v[88:89], v[96:97], v[152:153] op_sel_hi:[0,1,1]
	v_pk_fma_f32 v[94:95], v[88:89], v[94:95], v[154:155] op_sel_hi:[0,1,1]
	v_pk_fma_f32 v[82:83], v[84:85], v[94:95], v[82:83] op_sel_hi:[0,1,1]
	v_pk_fma_f32 v[112:113], v[84:85], v[96:97], v[112:113] op_sel_hi:[0,1,1]
	v_and_b32_e32 v84, 0xffff0000, v85
	v_exp_f32_e32 v84, v84
	v_and_b32_e32 v152, 0xffff0000, v89
	v_sub_f32_e32 v88, 1.0, v84
	v_pk_mul_f32 v[150:151], v[88:89], v[150:151] op_sel_hi:[0,1]
	v_pk_mul_f32 v[88:89], v[88:89], v[160:161] op_sel_hi:[0,1]
	v_pk_fma_f32 v[88:89], v[84:85], v[90:91], v[88:89] op_sel_hi:[0,1,1]
	v_pk_fma_f32 v[90:91], v[84:85], v[92:93], v[150:151] op_sel_hi:[0,1,1]
	v_pk_fma_f32 v[84:85], v[152:153], v[90:91], v[112:113] op_sel_hi:[0,1,1]
	v_pk_fma_f32 v[82:83], v[152:153], v[88:89], v[82:83] op_sel_hi:[0,1,1]
	ds_write_b128 v127, v[82:85] offset:8192
	s_waitcnt vmcnt(25)
	v_lshlrev_b32_e32 v83, 16, v74
	v_exp_f32_e32 v84, v83
	s_waitcnt vmcnt(23)
	v_lshlrev_b32_e32 v150, 16, v148
	v_and_b32_e32 v151, 0xffff0000, v148
	v_lshlrev_b32_e32 v148, 16, v149
	v_and_b32_e32 v149, 0xffff0000, v149
	v_sub_f32_e32 v92, 1.0, v84
	v_pk_mul_f32 v[112:113], v[92:93], v[150:151] op_sel_hi:[0,1]
	v_pk_mul_f32 v[92:93], v[92:93], v[148:149] op_sel_hi:[0,1]
	v_lshlrev_b32_e32 v82, 16, v78
	v_pk_fma_f32 v[92:93], v[84:85], v[100:101], v[92:93] op_sel_hi:[0,1,1]
	v_pk_fma_f32 v[100:101], v[84:85], v[104:105], v[112:113] op_sel_hi:[0,1,1]
	v_pk_fma_f32 v[84:85], v[82:83], v[100:101], 0 op_sel_hi:[0,1,0]
	v_pk_fma_f32 v[104:105], v[82:83], v[92:93], 0 op_sel_hi:[0,1,0]
	v_and_b32_e32 v82, 0xffff0000, v74
	v_and_b32_e32 v74, 0xffff0000, v78
	v_exp_f32_e32 v78, v82
	s_nop 0
	v_sub_f32_e32 v82, 1.0, v78
	v_pk_mul_f32 v[112:113], v[82:83], v[148:149] op_sel_hi:[0,1]
	v_pk_mul_f32 v[82:83], v[82:83], v[150:151] op_sel_hi:[0,1]
	v_pk_fma_f32 v[82:83], v[78:79], v[114:115], v[82:83] op_sel_hi:[0,1,1]
	v_pk_fma_f32 v[114:115], v[78:79], v[116:117], v[112:113] op_sel_hi:[0,1,1]
	v_lshlrev_b32_e32 v78, 16, v75
	v_exp_f32_e32 v78, v78
	v_pk_fma_f32 v[116:117], v[74:75], v[114:115], v[104:105] op_sel_hi:[0,1,1]
	v_pk_fma_f32 v[84:85], v[74:75], v[82:83], v[84:85] op_sel_hi:[0,1,1]
	v_lshlrev_b32_e32 v74, 16, v79
	v_sub_f32_e32 v104, 1.0, v78
	v_pk_mul_f32 v[112:113], v[104:105], v[150:151] op_sel_hi:[0,1]
	v_pk_mul_f32 v[104:105], v[104:105], v[148:149] op_sel_hi:[0,1]
	v_pk_fma_f32 v[104:105], v[78:79], v[120:121], v[104:105] op_sel_hi:[0,1,1]
	v_pk_fma_f32 v[112:113], v[78:79], v[118:119], v[112:113] op_sel_hi:[0,1,1]
	v_pk_fma_f32 v[84:85], v[74:75], v[112:113], v[84:85] op_sel_hi:[0,1,1]
	v_pk_fma_f32 v[118:119], v[74:75], v[104:105], v[116:117] op_sel_hi:[0,1,1]
	v_and_b32_e32 v75, 0xffff0000, v75
	v_exp_f32_e32 v116, v75
	v_and_b32_e32 v74, 0xffff0000, v79
	v_sub_f32_e32 v78, 1.0, v116
	v_pk_mul_f32 v[120:121], v[78:79], v[148:149] op_sel_hi:[0,1]
	v_pk_mul_f32 v[78:79], v[78:79], v[150:151] op_sel_hi:[0,1]
	v_pk_fma_f32 v[78:79], v[116:117], v[86:87], v[78:79] op_sel_hi:[0,1,1]
	v_pk_fma_f32 v[116:117], v[116:117], v[98:99], v[120:121] op_sel_hi:[0,1,1]
	v_pk_fma_f32 v[118:119], v[74:75], v[116:117], v[118:119] op_sel_hi:[0,1,1]
	v_pk_fma_f32 v[74:75], v[74:75], v[78:79], v[84:85] op_sel_hi:[0,1,1]
	v_lshlrev_b32_e32 v85, 16, v76
	v_exp_f32_e32 v98, v85
	v_lshlrev_b32_e32 v84, 16, v80
	v_sub_f32_e32 v86, 1.0, v98
	v_pk_mul_f32 v[120:121], v[86:87], v[150:151] op_sel_hi:[0,1]
	v_pk_mul_f32 v[86:87], v[86:87], v[148:149] op_sel_hi:[0,1]
	v_pk_fma_f32 v[86:87], v[98:99], v[102:103], v[86:87] op_sel_hi:[0,1,1]
	v_pk_fma_f32 v[98:99], v[98:99], v[110:111], v[120:121] op_sel_hi:[0,1,1]
	v_pk_fma_f32 v[74:75], v[84:85], v[98:99], v[74:75] op_sel_hi:[0,1,1]
	v_pk_fma_f32 v[110:111], v[84:85], v[86:87], v[118:119] op_sel_hi:[0,1,1]
	v_and_b32_e32 v84, 0xffff0000, v76
	v_and_b32_e32 v76, 0xffff0000, v80
	v_exp_f32_e32 v80, v84
	s_nop 0
	v_sub_f32_e32 v84, 1.0, v80
	v_pk_mul_f32 v[102:103], v[84:85], v[148:149] op_sel_hi:[0,1]
	v_pk_mul_f32 v[84:85], v[84:85], v[150:151] op_sel_hi:[0,1]
	v_pk_fma_f32 v[84:85], v[80:81], v[106:107], v[84:85] op_sel_hi:[0,1,1]
	v_pk_fma_f32 v[102:103], v[80:81], v[108:109], v[102:103] op_sel_hi:[0,1,1]
	v_lshlrev_b32_e32 v80, 16, v77
	v_exp_f32_e32 v80, v80
	v_pk_fma_f32 v[106:107], v[76:77], v[102:103], v[110:111] op_sel_hi:[0,1,1]
	v_pk_fma_f32 v[74:75], v[76:77], v[84:85], v[74:75] op_sel_hi:[0,1,1]
	v_lshlrev_b32_e32 v76, 16, v81
	v_sub_f32_e32 v108, 1.0, v80
	v_pk_mul_f32 v[110:111], v[108:109], v[150:151] op_sel_hi:[0,1]
	v_pk_mul_f32 v[108:109], v[108:109], v[148:149] op_sel_hi:[0,1]
	v_pk_fma_f32 v[96:97], v[80:81], v[96:97], v[108:109] op_sel_hi:[0,1,1]
	v_pk_fma_f32 v[94:95], v[80:81], v[94:95], v[110:111] op_sel_hi:[0,1,1]
	v_pk_fma_f32 v[74:75], v[76:77], v[94:95], v[74:75] op_sel_hi:[0,1,1]
	v_pk_fma_f32 v[106:107], v[76:77], v[96:97], v[106:107] op_sel_hi:[0,1,1]
	v_and_b32_e32 v76, 0xffff0000, v77
	v_exp_f32_e32 v76, v76
	v_and_b32_e32 v108, 0xffff0000, v81
	v_sub_f32_e32 v80, 1.0, v76
	v_pk_mul_f32 v[110:111], v[80:81], v[148:149] op_sel_hi:[0,1]
	v_pk_mul_f32 v[80:81], v[80:81], v[150:151] op_sel_hi:[0,1]
	v_pk_fma_f32 v[80:81], v[76:77], v[88:89], v[80:81] op_sel_hi:[0,1,1]
	v_pk_fma_f32 v[88:89], v[76:77], v[90:91], v[110:111] op_sel_hi:[0,1,1]
	v_pk_fma_f32 v[76:77], v[108:109], v[88:89], v[106:107] op_sel_hi:[0,1,1]
	v_pk_fma_f32 v[74:75], v[108:109], v[80:81], v[74:75] op_sel_hi:[0,1,1]
	ds_write_b128 v127, v[74:77] offset:16384
	s_waitcnt vmcnt(22)
	v_lshlrev_b32_e32 v74, 16, v66
	v_exp_f32_e32 v74, v74
	s_waitcnt vmcnt(20)
	v_lshlrev_b32_e32 v90, 16, v146
	v_and_b32_e32 v91, 0xffff0000, v146
	v_lshlrev_b32_e32 v106, 16, v147
	v_and_b32_e32 v107, 0xffff0000, v147
	v_sub_f32_e32 v76, 1.0, v74
	v_pk_mul_f32 v[110:111], v[76:77], v[90:91] op_sel_hi:[0,1]
	v_pk_mul_f32 v[76:77], v[76:77], v[106:107] op_sel_hi:[0,1]
	v_lshlrev_b32_e32 v108, 16, v70
	v_pk_fma_f32 v[76:77], v[74:75], v[92:93], v[76:77] op_sel_hi:[0,1,1]
	v_pk_fma_f32 v[74:75], v[74:75], v[100:101], v[110:111] op_sel_hi:[0,1,1]
	v_pk_fma_f32 v[92:93], v[108:109], v[74:75], 0 op_sel_hi:[0,1,0]
	v_pk_fma_f32 v[100:101], v[108:109], v[76:77], 0 op_sel_hi:[0,1,0]
	v_and_b32_e32 v108, 0xffff0000, v66
	v_and_b32_e32 v66, 0xffff0000, v70
	v_exp_f32_e32 v70, v108
	s_nop 0
	v_sub_f32_e32 v108, 1.0, v70
	v_pk_mul_f32 v[118:119], v[108:109], v[90:91] op_sel_hi:[0,1]
	v_pk_mul_f32 v[108:109], v[108:109], v[106:107] op_sel_hi:[0,1]
	v_pk_fma_f32 v[110:111], v[70:71], v[114:115], v[108:109] op_sel_hi:[0,1,1]
	v_pk_fma_f32 v[108:109], v[70:71], v[82:83], v[118:119] op_sel_hi:[0,1,1]
	v_lshlrev_b32_e32 v70, 16, v67
	v_exp_f32_e32 v70, v70
	v_pk_fma_f32 v[82:83], v[66:67], v[110:111], v[100:101] op_sel_hi:[0,1,1]
	v_pk_fma_f32 v[92:93], v[66:67], v[108:109], v[92:93] op_sel_hi:[0,1,1]
	v_lshlrev_b32_e32 v66, 16, v71
	v_sub_f32_e32 v100, 1.0, v70
	v_pk_mul_f32 v[118:119], v[100:101], v[90:91] op_sel_hi:[0,1]
	v_pk_mul_f32 v[100:101], v[100:101], v[106:107] op_sel_hi:[0,1]
	v_pk_fma_f32 v[114:115], v[70:71], v[104:105], v[100:101] op_sel_hi:[0,1,1]
	v_pk_fma_f32 v[112:113], v[70:71], v[112:113], v[118:119] op_sel_hi:[0,1,1]
	v_pk_fma_f32 v[92:93], v[66:67], v[112:113], v[92:93] op_sel_hi:[0,1,1]
	v_pk_fma_f32 v[82:83], v[66:67], v[114:115], v[82:83] op_sel_hi:[0,1,1]
	v_and_b32_e32 v67, 0xffff0000, v67
	v_exp_f32_e32 v70, v67
	v_and_b32_e32 v66, 0xffff0000, v71
	v_sub_f32_e32 v100, 1.0, v70
	v_pk_mul_f32 v[104:105], v[100:101], v[90:91] op_sel_hi:[0,1]
	v_pk_mul_f32 v[100:101], v[100:101], v[106:107] op_sel_hi:[0,1]
	v_pk_fma_f32 v[118:119], v[70:71], v[116:117], v[100:101] op_sel_hi:[0,1,1]
	v_pk_fma_f32 v[116:117], v[70:71], v[78:79], v[104:105] op_sel_hi:[0,1,1]
	v_lshlrev_b32_e32 v79, 16, v68
	v_pk_fma_f32 v[70:71], v[66:67], v[118:119], v[82:83] op_sel_hi:[0,1,1]
	v_exp_f32_e32 v82, v79
	v_pk_fma_f32 v[66:67], v[66:67], v[116:117], v[92:93] op_sel_hi:[0,1,1]
	v_lshlrev_b32_e32 v78, 16, v72
	v_sub_f32_e32 v92, 1.0, v82
	v_pk_mul_f32 v[104:105], v[92:93], v[90:91] op_sel_hi:[0,1]
	v_pk_mul_f32 v[92:93], v[92:93], v[106:107] op_sel_hi:[0,1]
	v_pk_fma_f32 v[100:101], v[82:83], v[86:87], v[92:93] op_sel_hi:[0,1,1]
	v_pk_fma_f32 v[98:99], v[82:83], v[98:99], v[104:105] op_sel_hi:[0,1,1]
	v_pk_fma_f32 v[66:67], v[78:79], v[98:99], v[66:67] op_sel_hi:[0,1,1]
	v_pk_fma_f32 v[70:71], v[78:79], v[100:101], v[70:71] op_sel_hi:[0,1,1]
	v_and_b32_e32 v78, 0xffff0000, v68
	v_and_b32_e32 v68, 0xffff0000, v72
	v_exp_f32_e32 v72, v78
	s_nop 0
	v_sub_f32_e32 v78, 1.0, v72
	v_pk_mul_f32 v[82:83], v[78:79], v[90:91] op_sel_hi:[0,1]
	v_pk_mul_f32 v[78:79], v[78:79], v[106:107] op_sel_hi:[0,1]
	v_pk_fma_f32 v[86:87], v[72:73], v[102:103], v[78:79] op_sel_hi:[0,1,1]
	v_pk_fma_f32 v[84:85], v[72:73], v[84:85], v[82:83] op_sel_hi:[0,1,1]
	v_lshlrev_b32_e32 v72, 16, v69
	v_exp_f32_e32 v72, v72
	v_pk_fma_f32 v[70:71], v[68:69], v[86:87], v[70:71] op_sel_hi:[0,1,1]
	v_pk_fma_f32 v[66:67], v[68:69], v[84:85], v[66:67] op_sel_hi:[0,1,1]
	v_lshlrev_b32_e32 v68, 16, v73
	v_sub_f32_e32 v78, 1.0, v72
	v_pk_mul_f32 v[82:83], v[78:79], v[90:91] op_sel_hi:[0,1]
	v_pk_mul_f32 v[78:79], v[78:79], v[106:107] op_sel_hi:[0,1]
	v_pk_fma_f32 v[94:95], v[72:73], v[94:95], v[82:83] op_sel_hi:[0,1,1]
	v_pk_fma_f32 v[96:97], v[72:73], v[96:97], v[78:79] op_sel_hi:[0,1,1]
	v_pk_fma_f32 v[78:79], v[68:69], v[94:95], v[66:67] op_sel_hi:[0,1,1]
	v_and_b32_e32 v66, 0xffff0000, v69
	v_exp_f32_e32 v66, v66
	v_pk_fma_f32 v[70:71], v[68:69], v[96:97], v[70:71] op_sel_hi:[0,1,1]
	v_and_b32_e32 v82, 0xffff0000, v73
	v_sub_f32_e32 v68, 1.0, v66
	v_pk_mul_f32 v[72:73], v[68:69], v[90:91] op_sel_hi:[0,1]
	v_pk_mul_f32 v[68:69], v[68:69], v[106:107] op_sel_hi:[0,1]
	v_pk_fma_f32 v[68:69], v[66:67], v[88:89], v[68:69] op_sel_hi:[0,1,1]
	v_pk_fma_f32 v[66:67], v[66:67], v[80:81], v[72:73] op_sel_hi:[0,1,1]
	v_pk_fma_f32 v[72:73], v[82:83], v[68:69], v[70:71] op_sel_hi:[0,1,1]
	v_pk_fma_f32 v[70:71], v[82:83], v[66:67], v[78:79] op_sel_hi:[0,1,1]
	ds_write_b128 v127, v[70:73] offset:24576
	s_cmp_gt_i32 s5, 3
	s_cbranch_scc1 .Lch_pre1
	s_mov_b32 s8, s4
	s_ashr_i32 s9, s8, 31
	s_ashr_i32 s11, s5, 31
	s_add_u32 s8, s8, s5
	s_addc_u32 s9, s9, s11
	s_add_u32 s8, s8, 0x4000
	s_addc_u32 s9, s9, 0
	s_mul_i32 s11, s9, 0x1600
	s_mul_hi_u32 s9, s8, 0x1600
	s_add_i32 s9, s9, s11
	s_mul_i32 s8, s8, 0x1600
	s_add_u32 s8, s52, s8
	s_addc_u32 s9, s53, s9
	s_mov_b32 s11, s1
	s_add_u32 s8, s8, s11
	s_addc_u32 s9, s9, 0
	s_add_u32 s8, s8, 0x1200
	s_addc_u32 s9, s9, 0
	v_lshlrev_b32_e32 v88, 1, v126
	v_mov_b32_e32 v89, v16
	v_lshl_add_u64 v[88:89], s[8:9], 0, v[88:89]
	global_load_dword v79, v[128:129], off
	global_load_dword v80, v[128:129], off offset:256
	global_load_ushort v81, v[88:89], off
	global_load_ushort v82, v[88:89], off offset:128
.Lch_pre1:
	v_lshl_add_u64 v[70:71], v[134:135], 0, v[130:131]
	global_store_dwordx4 v[70:71], v[74:77], off offset:-2048 sc1
	global_store_dwordx4 v[70:71], v[108:111], off offset:-1536 sc1
	global_store_dwordx4 v[70:71], v[112:115], off offset:-1024 sc1
	global_store_dwordx4 v[70:71], v[116:119], off offset:-512 sc1
	global_store_dwordx4 v[70:71], v[98:101], off sc1
	global_store_dwordx4 v[70:71], v[84:87], off offset:512 sc1
	global_store_dwordx4 v[70:71], v[94:97], off offset:1024 sc1
	global_store_dwordx4 v[70:71], v[66:69], off offset:1536 sc1
	s_waitcnt lgkmcnt(0)
	s_barrier
	ds_read2st64_b32 v[66:67], v167 offset1:2
	s_waitcnt lgkmcnt(0)
	v_add_f32_e32 v66, 0, v66
	v_add_f32_e32 v68, v66, v67
	ds_read2st64_b32 v[66:67], v167 offset0:4 offset1:6
	s_waitcnt lgkmcnt(0)
	v_add_f32_e32 v66, v68, v66
	v_add_f32_e32 v68, v66, v67
	ds_read2st64_b32 v[66:67], v167 offset0:8 offset1:10
	s_waitcnt lgkmcnt(0)
	v_add_f32_e32 v66, v68, v66
	v_add_f32_e32 v68, v66, v67
	ds_read2st64_b32 v[66:67], v167 offset0:12 offset1:14
	s_waitcnt lgkmcnt(0)
	v_add_f32_e32 v66, v68, v66
	v_add_f32_e32 v68, v66, v67
	ds_read2st64_b32 v[66:67], v167 offset0:16 offset1:18
	s_waitcnt lgkmcnt(0)
	v_add_f32_e32 v66, v68, v66
	v_add_f32_e32 v68, v66, v67
	ds_read2st64_b32 v[66:67], v167 offset0:20 offset1:22
	s_waitcnt lgkmcnt(0)
	v_add_f32_e32 v66, v68, v66
	v_add_f32_e32 v68, v66, v67
	ds_read2st64_b32 v[66:67], v167 offset0:24 offset1:26
	s_waitcnt lgkmcnt(0)
	v_add_f32_e32 v66, v68, v66
	v_add_f32_e32 v68, v66, v67
	ds_read2st64_b32 v[66:67], v167 offset0:28 offset1:30
	s_waitcnt lgkmcnt(0)
	v_add_f32_e32 v66, v68, v66
	v_add_f32_e32 v66, v66, v67
	ds_write_b32 v164, v66 offset:8192
	s_waitcnt lgkmcnt(0)
	s_barrier
	s_cmp_gt_i32 s5, 3
	s_cbranch_scc1 .LBB0_1194
	v_lshl_add_u32 v66, s5, 9, v165
	ds_read2st64_b32 v[66:67], v66 offset0:32 offset1:33
	v_and_b32_e32 v69, 64, v221
	v_add_u32_e32 v69, 64, v69
	v_xor_b32_e32 v70, 1, v221
	v_cmp_lt_i32_e32 vcc, v70, v69
	s_waitcnt lgkmcnt(0)
	v_mul_f32_e32 v68, v67, v67
	v_fmac_f32_e32 v68, v66, v66
	v_cndmask_b32_e32 v70, v221, v70, vcc
	v_lshlrev_b32_e32 v70, 2, v70
	ds_bpermute_b32 v70, v70, v68
	s_ashr_i32 s8, s4, 31
	s_ashr_i32 s9, s5, 31
	s_add_u32 s4, s4, s5
	s_addc_u32 s5, s8, s9
	s_waitcnt lgkmcnt(0)
	v_add_f32_e32 v68, v68, v70
	v_xor_b32_e32 v70, 2, v221
	v_cmp_lt_i32_e32 vcc, v70, v69
	s_add_u32 s4, s4, 0x4000
	s_addc_u32 s5, s5, 0
	v_cndmask_b32_e32 v70, v221, v70, vcc
	v_lshlrev_b32_e32 v70, 2, v70
	ds_bpermute_b32 v70, v70, v68
	s_mul_i32 s8, s5, 0x1600
	s_mul_hi_u32 s9, s4, 0x1600
	s_add_i32 s9, s9, s8
	s_mul_i32 s8, s4, 0x1600
	s_waitcnt lgkmcnt(0)
	v_add_f32_e32 v68, v68, v70
	v_xor_b32_e32 v70, 4, v221
	v_cmp_lt_i32_e32 vcc, v70, v69
	s_add_u32 s8, s52, s8
	s_addc_u32 s9, s53, s9
	v_cndmask_b32_e32 v70, v221, v70, vcc
	v_lshlrev_b32_e32 v70, 2, v70
	ds_bpermute_b32 v70, v70, v68
	s_add_u32 s8, s8, s1
	s_addc_u32 s9, s9, 0
	s_lshl_b64 s[4:5], s[4:5], 11
	s_add_u32 s4, s14, s4
	s_waitcnt lgkmcnt(0)
	v_add_f32_e32 v68, v68, v70
	v_xor_b32_e32 v70, 8, v221
	v_cmp_lt_i32_e32 vcc, v70, v69
	s_addc_u32 s5, s15, s5
	s_add_u32 s4, s4, s1
	v_cndmask_b32_e32 v70, v221, v70, vcc
	v_lshlrev_b32_e32 v70, 2, v70
	ds_bpermute_b32 v70, v70, v68
	s_addc_u32 s5, s5, 0
	s_waitcnt lgkmcnt(0)
	v_add_f32_e32 v68, v68, v70
	v_xor_b32_e32 v70, 16, v221
	v_cmp_lt_i32_e32 vcc, v70, v69
	s_nop 1
	v_cndmask_b32_e32 v70, v221, v70, vcc
	v_lshlrev_b32_e32 v70, 2, v70
	ds_bpermute_b32 v70, v70, v68
	s_waitcnt lgkmcnt(0)
	v_add_f32_e32 v68, v68, v70
	v_xor_b32_e32 v70, 32, v221
	v_cmp_lt_i32_e32 vcc, v70, v69
	s_nop 1
	v_cndmask_b32_e32 v69, v221, v70, vcc
	v_lshlrev_b32_e32 v69, 2, v69
	ds_bpermute_b32 v69, v69, v68
	s_waitcnt lgkmcnt(0)
	v_add_f32_e32 v68, v68, v69
	v_fmamk_f32 v68, v68, 0x3c000000, v218
	v_rsq_f32_e32 v74, v68
	v_lshlrev_b32_e32 v76, 1, v126
	v_mul_f32_e32 v66, v66, v74
	v_mul_f32_e32 v67, v67, v74
	s_waitcnt vmcnt(8)
	v_mul_f32_e32 v66, v79, v66
	v_lshlrev_b32_e32 v81, 16, v81
	v_mul_f32_e32 v66, v66, v81
	v_cvt_pk_bf16_f32 v66, v66, v66
	global_store_short v76, v66, s[4:5] offset:1024
	v_mul_f32_e32 v67, v80, v67
	v_lshlrev_b32_e32 v82, 16, v82
	v_mul_f32_e32 v67, v67, v82
	v_cvt_pk_bf16_f32 v67, v67, v67
	global_store_short v76, v67, s[4:5] offset:1152
.LBB0_1194:
	s_waitcnt lgkmcnt(0)
	s_barrier
	s_andn2_b64 vcc, exec, s[2:3]
	s_cbranch_vccnz .LBB0_1191
	s_waitcnt vmcnt(19)
	v_lshlrev_b32_e32 v68, 16, v38
	v_exp_f32_e32 v68, v68
	v_and_b32_e32 v38, 0xffff0000, v38
	v_exp_f32_e32 v38, v38
	s_waitcnt vmcnt(17)
	v_lshlrev_b32_e32 v66, 16, v144
	v_and_b32_e32 v67, 0xffff0000, v144
	v_lshlrev_b32_e32 v70, 16, v145
	v_and_b32_e32 v71, 0xffff0000, v145
	v_sub_f32_e32 v74, 1.0, v68
	v_pk_mul_f32 v[76:77], v[74:75], v[66:67] op_sel_hi:[0,1]
	v_pk_mul_f32 v[74:75], v[74:75], v[70:71] op_sel_hi:[0,1]
	v_pk_fma_f32 v[64:65], v[64:65], v[68:69], v[74:75] op_sel_hi:[1,0,1]
	v_sub_f32_e32 v74, 1.0, v38
	v_pk_fma_f32 v[62:63], v[62:63], v[68:69], v[76:77] op_sel_hi:[1,0,1]
	v_pk_mul_f32 v[76:77], v[74:75], v[70:71] op_sel_hi:[0,1]
	v_pk_mul_f32 v[74:75], v[74:75], v[66:67] op_sel_hi:[0,1]
	v_pk_fma_f32 v[58:59], v[58:59], v[38:39], v[74:75] op_sel_hi:[1,0,1]
	v_pk_fma_f32 v[60:61], v[60:61], v[38:39], v[76:77] op_sel_hi:[1,0,1]
	v_lshlrev_b32_e32 v38, 16, v39
	v_exp_f32_e32 v38, v38
	v_lshlrev_b32_e32 v72, 16, v34
	v_pk_fma_f32 v[68:69], v[72:73], v[62:63], 0 op_sel_hi:[0,1,0]
	v_pk_fma_f32 v[72:73], v[72:73], v[64:65], 0 op_sel_hi:[0,1,0]
	v_sub_f32_e32 v74, 1.0, v38
	v_pk_mul_f32 v[76:77], v[74:75], v[66:67] op_sel_hi:[0,1]
	v_pk_mul_f32 v[74:75], v[74:75], v[70:71] op_sel_hi:[0,1]
	v_pk_fma_f32 v[56:57], v[56:57], v[38:39], v[74:75] op_sel_hi:[1,0,1]
	v_pk_fma_f32 v[54:55], v[54:55], v[38:39], v[76:77] op_sel_hi:[1,0,1]
	v_and_b32_e32 v38, 0xffff0000, v39
	v_exp_f32_e32 v38, v38
	v_and_b32_e32 v34, 0xffff0000, v34
	v_pk_fma_f32 v[72:73], v[34:35], v[60:61], v[72:73] op_sel_hi:[0,1,1]
	v_pk_fma_f32 v[68:69], v[34:35], v[58:59], v[68:69] op_sel_hi:[0,1,1]
	v_lshlrev_b32_e32 v34, 16, v35
	v_sub_f32_e32 v74, 1.0, v38
	v_pk_fma_f32 v[68:69], v[34:35], v[54:55], v[68:69] op_sel_hi:[0,1,1]
	v_pk_fma_f32 v[72:73], v[34:35], v[56:57], v[72:73] op_sel_hi:[0,1,1]
	v_and_b32_e32 v34, 0xffff0000, v35
	v_pk_mul_f32 v[76:77], v[74:75], v[70:71] op_sel_hi:[0,1]
	v_pk_mul_f32 v[74:75], v[74:75], v[66:67] op_sel_hi:[0,1]
	v_lshlrev_b32_e32 v35, 16, v40
	v_pk_fma_f32 v[50:51], v[50:51], v[38:39], v[74:75] op_sel_hi:[1,0,1]
	v_pk_fma_f32 v[38:39], v[52:53], v[38:39], v[76:77] op_sel_hi:[1,0,1]
	v_exp_f32_e32 v52, v35
	v_and_b32_e32 v40, 0xffff0000, v40
	v_exp_f32_e32 v40, v40
	v_pk_fma_f32 v[72:73], v[34:35], v[38:39], v[72:73] op_sel_hi:[0,1,1]
	v_sub_f32_e32 v74, 1.0, v52
	v_pk_mul_f32 v[76:77], v[74:75], v[66:67] op_sel_hi:[0,1]
	v_pk_mul_f32 v[74:75], v[74:75], v[70:71] op_sel_hi:[0,1]
	v_pk_fma_f32 v[34:35], v[34:35], v[50:51], v[68:69] op_sel_hi:[0,1,1]
	v_lshlrev_b32_e32 v68, 16, v36
	v_pk_fma_f32 v[48:49], v[48:49], v[52:53], v[74:75] op_sel_hi:[1,0,1]
	v_pk_fma_f32 v[46:47], v[46:47], v[52:53], v[76:77] op_sel_hi:[1,0,1]
	v_pk_fma_f32 v[52:53], v[68:69], v[48:49], v[72:73] op_sel_hi:[0,1,1]
	v_pk_fma_f32 v[34:35], v[68:69], v[46:47], v[34:35] op_sel_hi:[0,1,1]
	v_sub_f32_e32 v68, 1.0, v40
	v_pk_mul_f32 v[72:73], v[68:69], v[70:71] op_sel_hi:[0,1]
	v_pk_mul_f32 v[68:69], v[68:69], v[66:67] op_sel_hi:[0,1]
	v_pk_fma_f32 v[42:43], v[42:43], v[40:41], v[68:69] op_sel_hi:[1,0,1]
	v_pk_fma_f32 v[44:45], v[44:45], v[40:41], v[72:73] op_sel_hi:[1,0,1]
	v_lshlrev_b32_e32 v40, 16, v41
	v_exp_f32_e32 v40, v40
	v_and_b32_e32 v36, 0xffff0000, v36
	v_pk_fma_f32 v[52:53], v[36:37], v[44:45], v[52:53] op_sel_hi:[0,1,1]
	v_pk_fma_f32 v[34:35], v[36:37], v[42:43], v[34:35] op_sel_hi:[0,1,1]
	v_sub_f32_e32 v68, 1.0, v40
	v_pk_mul_f32 v[72:73], v[68:69], v[66:67] op_sel_hi:[0,1]
	v_pk_mul_f32 v[68:69], v[68:69], v[70:71] op_sel_hi:[0,1]
	v_pk_fma_f32 v[32:33], v[32:33], v[40:41], v[68:69] op_sel_hi:[1,0,1]
	v_pk_fma_f32 v[30:31], v[30:31], v[40:41], v[72:73] op_sel_hi:[1,0,1]
	v_and_b32_e32 v40, 0xffff0000, v41
	v_exp_f32_e32 v40, v40
	v_lshlrev_b32_e32 v36, 16, v37
	v_pk_fma_f32 v[34:35], v[36:37], v[30:31], v[34:35] op_sel_hi:[0,1,1]
	v_pk_fma_f32 v[52:53], v[36:37], v[32:33], v[52:53] op_sel_hi:[0,1,1]
	v_sub_f32_e32 v68, 1.0, v40
	v_pk_mul_f32 v[70:71], v[68:69], v[70:71] op_sel_hi:[0,1]
	v_pk_mul_f32 v[66:67], v[68:69], v[66:67] op_sel_hi:[0,1]
	v_and_b32_e32 v36, 0xffff0000, v37
	v_pk_fma_f32 v[66:67], v[26:27], v[40:41], v[66:67] op_sel_hi:[1,0,1]
	v_pk_fma_f32 v[40:41], v[28:29], v[40:41], v[70:71] op_sel_hi:[1,0,1]
	v_pk_fma_f32 v[26:27], v[36:37], v[66:67], v[34:35] op_sel_hi:[0,1,1]
	v_pk_fma_f32 v[28:29], v[36:37], v[40:41], v[52:53] op_sel_hi:[0,1,1]
	ds_write_b128 v127, v[26:29]
	s_waitcnt vmcnt(16)
	v_lshlrev_b32_e32 v28, 16, v22
	v_exp_f32_e32 v28, v28
	v_and_b32_e32 v22, 0xffff0000, v22
	v_exp_f32_e32 v22, v22
	s_waitcnt vmcnt(14)
	v_lshlrev_b32_e32 v26, 16, v142
	v_and_b32_e32 v27, 0xffff0000, v142
	v_lshlrev_b32_e32 v34, 16, v143
	v_and_b32_e32 v35, 0xffff0000, v143
	v_sub_f32_e32 v52, 1.0, v28
	v_pk_mul_f32 v[68:69], v[52:53], v[26:27] op_sel_hi:[0,1]
	v_pk_mul_f32 v[52:53], v[52:53], v[34:35] op_sel_hi:[0,1]
	v_pk_fma_f32 v[52:53], v[28:29], v[64:65], v[52:53] op_sel_hi:[0,1,1]
	v_sub_f32_e32 v64, 1.0, v22
	v_pk_fma_f32 v[28:29], v[28:29], v[62:63], v[68:69] op_sel_hi:[0,1,1]
	v_pk_mul_f32 v[68:69], v[64:65], v[34:35] op_sel_hi:[0,1]
	v_pk_mul_f32 v[64:65], v[64:65], v[26:27] op_sel_hi:[0,1]
	v_pk_fma_f32 v[58:59], v[22:23], v[58:59], v[64:65] op_sel_hi:[0,1,1]
	v_pk_fma_f32 v[60:61], v[22:23], v[60:61], v[68:69] op_sel_hi:[0,1,1]
	v_lshlrev_b32_e32 v22, 16, v23
	v_exp_f32_e32 v22, v22
	v_lshlrev_b32_e32 v36, 16, v18
	v_pk_fma_f32 v[62:63], v[36:37], v[28:29], 0 op_sel_hi:[0,1,0]
	v_pk_fma_f32 v[36:37], v[36:37], v[52:53], 0 op_sel_hi:[0,1,0]
	v_sub_f32_e32 v64, 1.0, v22
	v_pk_mul_f32 v[68:69], v[64:65], v[26:27] op_sel_hi:[0,1]
	v_pk_mul_f32 v[64:65], v[64:65], v[34:35] op_sel_hi:[0,1]
	v_pk_fma_f32 v[56:57], v[22:23], v[56:57], v[64:65] op_sel_hi:[0,1,1]
	v_pk_fma_f32 v[54:55], v[22:23], v[54:55], v[68:69] op_sel_hi:[0,1,1]
	v_and_b32_e32 v22, 0xffff0000, v23
	v_exp_f32_e32 v22, v22
	v_and_b32_e32 v18, 0xffff0000, v18
	v_pk_fma_f32 v[36:37], v[18:19], v[60:61], v[36:37] op_sel_hi:[0,1,1]
	v_pk_fma_f32 v[62:63], v[18:19], v[58:59], v[62:63] op_sel_hi:[0,1,1]
	v_lshlrev_b32_e32 v18, 16, v19
	v_sub_f32_e32 v64, 1.0, v22
	v_pk_fma_f32 v[62:63], v[18:19], v[54:55], v[62:63] op_sel_hi:[0,1,1]
	v_pk_fma_f32 v[36:37], v[18:19], v[56:57], v[36:37] op_sel_hi:[0,1,1]
	v_and_b32_e32 v18, 0xffff0000, v19
	v_pk_mul_f32 v[68:69], v[64:65], v[34:35] op_sel_hi:[0,1]
	v_pk_mul_f32 v[64:65], v[64:65], v[26:27] op_sel_hi:[0,1]
	v_lshlrev_b32_e32 v19, 16, v24
	v_pk_fma_f32 v[50:51], v[22:23], v[50:51], v[64:65] op_sel_hi:[0,1,1]
	v_pk_fma_f32 v[22:23], v[22:23], v[38:39], v[68:69] op_sel_hi:[0,1,1]
	v_exp_f32_e32 v38, v19
	v_and_b32_e32 v24, 0xffff0000, v24
	v_exp_f32_e32 v24, v24
	v_pk_fma_f32 v[36:37], v[18:19], v[22:23], v[36:37] op_sel_hi:[0,1,1]
	v_sub_f32_e32 v64, 1.0, v38
	v_pk_mul_f32 v[68:69], v[64:65], v[26:27] op_sel_hi:[0,1]
	v_pk_mul_f32 v[64:65], v[64:65], v[34:35] op_sel_hi:[0,1]
	v_pk_fma_f32 v[18:19], v[18:19], v[50:51], v[62:63] op_sel_hi:[0,1,1]
	v_lshlrev_b32_e32 v62, 16, v20
	v_pk_fma_f32 v[48:49], v[38:39], v[48:49], v[64:65] op_sel_hi:[0,1,1]
	v_pk_fma_f32 v[38:39], v[38:39], v[46:47], v[68:69] op_sel_hi:[0,1,1]
	v_sub_f32_e32 v46, 1.0, v24
	v_pk_fma_f32 v[18:19], v[62:63], v[38:39], v[18:19] op_sel_hi:[0,1,1]
	v_pk_fma_f32 v[36:37], v[62:63], v[48:49], v[36:37] op_sel_hi:[0,1,1]
	v_pk_mul_f32 v[62:63], v[46:47], v[34:35] op_sel_hi:[0,1]
	v_pk_mul_f32 v[46:47], v[46:47], v[26:27] op_sel_hi:[0,1]
	v_pk_fma_f32 v[42:43], v[24:25], v[42:43], v[46:47] op_sel_hi:[0,1,1]
	v_pk_fma_f32 v[44:45], v[24:25], v[44:45], v[62:63] op_sel_hi:[0,1,1]
	v_lshlrev_b32_e32 v24, 16, v25
	v_exp_f32_e32 v24, v24
	v_and_b32_e32 v20, 0xffff0000, v20
	v_pk_fma_f32 v[36:37], v[20:21], v[44:45], v[36:37] op_sel_hi:[0,1,1]
	v_pk_fma_f32 v[18:19], v[20:21], v[42:43], v[18:19] op_sel_hi:[0,1,1]
	v_sub_f32_e32 v46, 1.0, v24
	v_pk_mul_f32 v[62:63], v[46:47], v[26:27] op_sel_hi:[0,1]
	v_pk_mul_f32 v[46:47], v[46:47], v[34:35] op_sel_hi:[0,1]
	v_pk_fma_f32 v[32:33], v[24:25], v[32:33], v[46:47] op_sel_hi:[0,1,1]
	v_pk_fma_f32 v[30:31], v[24:25], v[30:31], v[62:63] op_sel_hi:[0,1,1]
	v_and_b32_e32 v24, 0xffff0000, v25
	v_exp_f32_e32 v24, v24
	v_lshlrev_b32_e32 v20, 16, v21
	v_pk_fma_f32 v[18:19], v[20:21], v[30:31], v[18:19] op_sel_hi:[0,1,1]
	v_pk_fma_f32 v[36:37], v[20:21], v[32:33], v[36:37] op_sel_hi:[0,1,1]
	v_sub_f32_e32 v20, 1.0, v24
	v_and_b32_e32 v46, 0xffff0000, v21
	v_pk_mul_f32 v[34:35], v[20:21], v[34:35] op_sel_hi:[0,1]
	v_pk_mul_f32 v[20:21], v[20:21], v[26:27] op_sel_hi:[0,1]
	v_pk_fma_f32 v[26:27], v[24:25], v[66:67], v[20:21] op_sel_hi:[0,1,1]
	v_pk_fma_f32 v[24:25], v[24:25], v[40:41], v[34:35] op_sel_hi:[0,1,1]
	v_pk_fma_f32 v[20:21], v[46:47], v[24:25], v[36:37] op_sel_hi:[0,1,1]
	v_pk_fma_f32 v[18:19], v[46:47], v[26:27], v[18:19] op_sel_hi:[0,1,1]
	ds_write_b128 v127, v[18:21] offset:8192
	s_waitcnt vmcnt(13)
	v_lshlrev_b32_e32 v20, 16, v12
	v_exp_f32_e32 v20, v20
	v_and_b32_e32 v12, 0xffff0000, v12
	v_exp_f32_e32 v12, v12
	s_waitcnt vmcnt(11)
	v_lshlrev_b32_e32 v18, 16, v140
	v_and_b32_e32 v19, 0xffff0000, v140
	v_lshlrev_b32_e32 v34, 16, v141
	v_and_b32_e32 v35, 0xffff0000, v141
	v_sub_f32_e32 v40, 1.0, v20
	v_pk_mul_f32 v[46:47], v[40:41], v[18:19] op_sel_hi:[0,1]
	v_pk_mul_f32 v[40:41], v[40:41], v[34:35] op_sel_hi:[0,1]
	v_pk_fma_f32 v[40:41], v[20:21], v[52:53], v[40:41] op_sel_hi:[0,1,1]
	v_pk_fma_f32 v[20:21], v[20:21], v[28:29], v[46:47] op_sel_hi:[0,1,1]
	v_sub_f32_e32 v46, 1.0, v12
	v_pk_mul_f32 v[52:53], v[46:47], v[34:35] op_sel_hi:[0,1]
	v_pk_mul_f32 v[46:47], v[46:47], v[18:19] op_sel_hi:[0,1]
	v_pk_fma_f32 v[46:47], v[12:13], v[58:59], v[46:47] op_sel_hi:[0,1,1]
	v_pk_fma_f32 v[52:53], v[12:13], v[60:61], v[52:53] op_sel_hi:[0,1,1]
	v_lshlrev_b32_e32 v12, 16, v13
	v_exp_f32_e32 v12, v12
	v_lshlrev_b32_e32 v36, 16, v8
	v_pk_fma_f32 v[28:29], v[36:37], v[20:21], 0 op_sel_hi:[0,1,0]
	v_pk_fma_f32 v[36:37], v[36:37], v[40:41], 0 op_sel_hi:[0,1,0]
	v_sub_f32_e32 v58, 1.0, v12
	v_pk_mul_f32 v[60:61], v[58:59], v[18:19] op_sel_hi:[0,1]
	v_pk_mul_f32 v[58:59], v[58:59], v[34:35] op_sel_hi:[0,1]
	v_pk_fma_f32 v[56:57], v[12:13], v[56:57], v[58:59] op_sel_hi:[0,1,1]
	v_pk_fma_f32 v[54:55], v[12:13], v[54:55], v[60:61] op_sel_hi:[0,1,1]
	v_and_b32_e32 v12, 0xffff0000, v13
	v_exp_f32_e32 v12, v12
	v_and_b32_e32 v8, 0xffff0000, v8
	v_pk_fma_f32 v[36:37], v[8:9], v[52:53], v[36:37] op_sel_hi:[0,1,1]
	v_pk_fma_f32 v[28:29], v[8:9], v[46:47], v[28:29] op_sel_hi:[0,1,1]
	v_lshlrev_b32_e32 v8, 16, v9
	v_sub_f32_e32 v58, 1.0, v12
	v_pk_fma_f32 v[28:29], v[8:9], v[54:55], v[28:29] op_sel_hi:[0,1,1]
	v_pk_fma_f32 v[36:37], v[8:9], v[56:57], v[36:37] op_sel_hi:[0,1,1]
	v_and_b32_e32 v8, 0xffff0000, v9
	v_pk_mul_f32 v[60:61], v[58:59], v[34:35] op_sel_hi:[0,1]
	v_pk_mul_f32 v[58:59], v[58:59], v[18:19] op_sel_hi:[0,1]
	v_lshlrev_b32_e32 v9, 16, v14
	v_pk_fma_f32 v[50:51], v[12:13], v[50:51], v[58:59] op_sel_hi:[0,1,1]
	v_pk_fma_f32 v[22:23], v[12:13], v[22:23], v[60:61] op_sel_hi:[0,1,1]
	v_exp_f32_e32 v12, v9
	v_pk_fma_f32 v[36:37], v[8:9], v[22:23], v[36:37] op_sel_hi:[0,1,1]
	v_pk_fma_f32 v[8:9], v[8:9], v[50:51], v[28:29] op_sel_hi:[0,1,1]
	v_lshlrev_b32_e32 v28, 16, v10
	v_sub_f32_e32 v58, 1.0, v12
	v_pk_mul_f32 v[60:61], v[58:59], v[18:19] op_sel_hi:[0,1]
	v_pk_mul_f32 v[58:59], v[58:59], v[34:35] op_sel_hi:[0,1]
	v_pk_fma_f32 v[48:49], v[12:13], v[48:49], v[58:59] op_sel_hi:[0,1,1]
	v_pk_fma_f32 v[38:39], v[12:13], v[38:39], v[60:61] op_sel_hi:[0,1,1]
	v_and_b32_e32 v12, 0xffff0000, v14
	v_exp_f32_e32 v12, v12
	v_pk_fma_f32 v[8:9], v[28:29], v[38:39], v[8:9] op_sel_hi:[0,1,1]
	v_pk_fma_f32 v[28:29], v[28:29], v[48:49], v[36:37] op_sel_hi:[0,1,1]
	v_and_b32_e32 v10, 0xffff0000, v10
	v_sub_f32_e32 v14, 1.0, v12
	v_pk_mul_f32 v[36:37], v[14:15], v[34:35] op_sel_hi:[0,1]
	v_pk_mul_f32 v[58:59], v[14:15], v[18:19] op_sel_hi:[0,1]
	v_pk_fma_f32 v[42:43], v[12:13], v[42:43], v[58:59] op_sel_hi:[0,1,1]
	v_pk_fma_f32 v[36:37], v[12:13], v[44:45], v[36:37] op_sel_hi:[0,1,1]
	v_lshlrev_b32_e32 v12, 16, v15
	v_exp_f32_e32 v12, v12
	v_pk_fma_f32 v[28:29], v[10:11], v[36:37], v[28:29] op_sel_hi:[0,1,1]
	v_pk_fma_f32 v[8:9], v[10:11], v[42:43], v[8:9] op_sel_hi:[0,1,1]
	v_lshlrev_b32_e32 v10, 16, v11
	v_sub_f32_e32 v14, 1.0, v12
	v_pk_mul_f32 v[44:45], v[14:15], v[18:19] op_sel_hi:[0,1]
	v_pk_mul_f32 v[58:59], v[14:15], v[34:35] op_sel_hi:[0,1]
	v_pk_fma_f32 v[58:59], v[12:13], v[32:33], v[58:59] op_sel_hi:[0,1,1]
	v_pk_fma_f32 v[44:45], v[12:13], v[30:31], v[44:45] op_sel_hi:[0,1,1]
	v_and_b32_e32 v12, 0xffff0000, v15
	v_exp_f32_e32 v12, v12
	v_pk_fma_f32 v[8:9], v[10:11], v[44:45], v[8:9] op_sel_hi:[0,1,1]
	v_pk_fma_f32 v[14:15], v[10:11], v[58:59], v[28:29] op_sel_hi:[0,1,1]
	v_and_b32_e32 v28, 0xffff0000, v11
	v_sub_f32_e32 v10, 1.0, v12
	v_pk_mul_f32 v[30:31], v[10:11], v[34:35] op_sel_hi:[0,1]
	v_pk_mul_f32 v[10:11], v[10:11], v[18:19] op_sel_hi:[0,1]
	v_pk_fma_f32 v[60:61], v[12:13], v[26:27], v[10:11] op_sel_hi:[0,1,1]
	v_pk_fma_f32 v[62:63], v[12:13], v[24:25], v[30:31] op_sel_hi:[0,1,1]
	v_pk_fma_f32 v[10:11], v[28:29], v[62:63], v[14:15] op_sel_hi:[0,1,1]
	v_pk_fma_f32 v[8:9], v[28:29], v[60:61], v[8:9] op_sel_hi:[0,1,1]
	ds_write_b128 v127, v[8:11] offset:16384
	s_waitcnt vmcnt(10)
	v_lshlrev_b32_e32 v8, 16, v4
	v_exp_f32_e32 v8, v8
	v_and_b32_e32 v4, 0xffff0000, v4
	v_exp_f32_e32 v4, v4
	s_waitcnt vmcnt(8)
	v_lshlrev_b32_e32 v64, 16, v138
	v_and_b32_e32 v65, 0xffff0000, v138
	v_lshlrev_b32_e32 v66, 16, v139
	v_and_b32_e32 v67, 0xffff0000, v139
	v_sub_f32_e32 v10, 1.0, v8
	v_pk_mul_f32 v[14:15], v[10:11], v[64:65] op_sel_hi:[0,1]
	v_pk_mul_f32 v[10:11], v[10:11], v[66:67] op_sel_hi:[0,1]
	v_lshlrev_b32_e32 v12, 16, v0
	v_pk_fma_f32 v[10:11], v[8:9], v[40:41], v[10:11] op_sel_hi:[0,1,1]
	v_pk_fma_f32 v[8:9], v[8:9], v[20:21], v[14:15] op_sel_hi:[0,1,1]
	v_pk_fma_f32 v[18:19], v[12:13], v[8:9], 0 op_sel_hi:[0,1,0]
	v_pk_fma_f32 v[20:21], v[12:13], v[10:11], 0 op_sel_hi:[0,1,0]
	v_sub_f32_e32 v12, 1.0, v4
	v_pk_mul_f32 v[24:25], v[12:13], v[64:65] op_sel_hi:[0,1]
	v_pk_mul_f32 v[12:13], v[12:13], v[66:67] op_sel_hi:[0,1]
	v_pk_fma_f32 v[14:15], v[4:5], v[52:53], v[12:13] op_sel_hi:[0,1,1]
	v_pk_fma_f32 v[12:13], v[4:5], v[46:47], v[24:25] op_sel_hi:[0,1,1]
	v_lshlrev_b32_e32 v4, 16, v5
	v_exp_f32_e32 v4, v4
	v_and_b32_e32 v0, 0xffff0000, v0
	v_pk_fma_f32 v[26:27], v[0:1], v[12:13], v[18:19] op_sel_hi:[0,1,1]
	v_pk_fma_f32 v[24:25], v[0:1], v[14:15], v[20:21] op_sel_hi:[0,1,1]
	v_sub_f32_e32 v18, 1.0, v4
	v_pk_mul_f32 v[28:29], v[18:19], v[64:65] op_sel_hi:[0,1]
	v_pk_mul_f32 v[18:19], v[18:19], v[66:67] op_sel_hi:[0,1]
	v_pk_fma_f32 v[20:21], v[4:5], v[56:57], v[18:19] op_sel_hi:[0,1,1]
	v_pk_fma_f32 v[18:19], v[4:5], v[54:55], v[28:29] op_sel_hi:[0,1,1]
	v_and_b32_e32 v4, 0xffff0000, v5
	v_exp_f32_e32 v4, v4
	v_lshlrev_b32_e32 v0, 16, v1
	v_pk_fma_f32 v[28:29], v[0:1], v[20:21], v[24:25] op_sel_hi:[0,1,1]
	v_pk_fma_f32 v[26:27], v[0:1], v[18:19], v[26:27] op_sel_hi:[0,1,1]
	v_sub_f32_e32 v24, 1.0, v4
	v_and_b32_e32 v0, 0xffff0000, v1
	v_pk_mul_f32 v[30:31], v[24:25], v[64:65] op_sel_hi:[0,1]
	v_pk_mul_f32 v[24:25], v[24:25], v[66:67] op_sel_hi:[0,1]
	v_lshlrev_b32_e32 v1, 16, v6
	v_pk_fma_f32 v[24:25], v[4:5], v[22:23], v[24:25] op_sel_hi:[0,1,1]
	v_pk_fma_f32 v[22:23], v[4:5], v[50:51], v[30:31] op_sel_hi:[0,1,1]
	v_exp_f32_e32 v4, v1
	v_pk_fma_f32 v[30:31], v[0:1], v[24:25], v[28:29] op_sel_hi:[0,1,1]
	v_pk_fma_f32 v[0:1], v[0:1], v[22:23], v[26:27] op_sel_hi:[0,1,1]
	v_lshlrev_b32_e32 v32, 16, v2
	v_sub_f32_e32 v26, 1.0, v4
	v_pk_mul_f32 v[34:35], v[26:27], v[64:65] op_sel_hi:[0,1]
	v_pk_mul_f32 v[26:27], v[26:27], v[66:67] op_sel_hi:[0,1]
	v_pk_fma_f32 v[28:29], v[4:5], v[48:49], v[26:27] op_sel_hi:[0,1,1]
	v_pk_fma_f32 v[26:27], v[4:5], v[38:39], v[34:35] op_sel_hi:[0,1,1]
	v_and_b32_e32 v4, 0xffff0000, v6
	v_exp_f32_e32 v4, v4
	v_pk_fma_f32 v[0:1], v[32:33], v[26:27], v[0:1] op_sel_hi:[0,1,1]
	v_pk_fma_f32 v[34:35], v[32:33], v[28:29], v[30:31] op_sel_hi:[0,1,1]
	v_and_b32_e32 v2, 0xffff0000, v2
	v_sub_f32_e32 v6, 1.0, v4
	v_pk_mul_f32 v[30:31], v[6:7], v[64:65] op_sel_hi:[0,1]
	v_pk_mul_f32 v[32:33], v[6:7], v[66:67] op_sel_hi:[0,1]
	v_pk_fma_f32 v[32:33], v[4:5], v[36:37], v[32:33] op_sel_hi:[0,1,1]
	v_pk_fma_f32 v[30:31], v[4:5], v[42:43], v[30:31] op_sel_hi:[0,1,1]
	v_lshlrev_b32_e32 v4, 16, v7
	v_exp_f32_e32 v4, v4
	v_pk_fma_f32 v[38:39], v[2:3], v[32:33], v[34:35] op_sel_hi:[0,1,1]
	v_pk_fma_f32 v[0:1], v[2:3], v[30:31], v[0:1] op_sel_hi:[0,1,1]
	v_lshlrev_b32_e32 v2, 16, v3
	v_sub_f32_e32 v6, 1.0, v4
	v_pk_mul_f32 v[34:35], v[6:7], v[64:65] op_sel_hi:[0,1]
	v_pk_mul_f32 v[36:37], v[6:7], v[66:67] op_sel_hi:[0,1]
	v_pk_fma_f32 v[36:37], v[4:5], v[58:59], v[36:37] op_sel_hi:[0,1,1]
	v_pk_fma_f32 v[34:35], v[4:5], v[44:45], v[34:35] op_sel_hi:[0,1,1]
	v_and_b32_e32 v4, 0xffff0000, v7
	v_exp_f32_e32 v4, v4
	v_pk_fma_f32 v[40:41], v[2:3], v[34:35], v[0:1] op_sel_hi:[0,1,1]
	v_pk_fma_f32 v[6:7], v[2:3], v[36:37], v[38:39] op_sel_hi:[0,1,1]
	v_and_b32_e32 v38, 0xffff0000, v3
	v_sub_f32_e32 v0, 1.0, v4
	v_pk_mul_f32 v[42:43], v[0:1], v[64:65] op_sel_hi:[0,1]
	v_pk_mul_f32 v[0:1], v[0:1], v[66:67] op_sel_hi:[0,1]
	v_pk_fma_f32 v[2:3], v[4:5], v[62:63], v[0:1] op_sel_hi:[0,1,1]
	v_pk_fma_f32 v[0:1], v[4:5], v[60:61], v[42:43] op_sel_hi:[0,1,1]
	s_ashr_i32 s1, s0, 31
	v_pk_fma_f32 v[6:7], v[38:39], v[2:3], v[6:7] op_sel_hi:[0,1,1]
	v_pk_fma_f32 v[4:5], v[38:39], v[0:1], v[40:41] op_sel_hi:[0,1,1]
	s_lshl_b64 s[2:3], s[0:1], 16
	ds_write_b128 v127, v[4:7] offset:24576
	v_readfirstlane_b32 s10, v17
	s_ashr_i32 s10, s10, 6
	s_cmp_gt_i32 s10, 3
	s_cbranch_scc1 .Lch_pre2
	s_and_b32 s8, s0, -4
	s_ashr_i32 s9, s8, 31
	s_ashr_i32 s11, s10, 31
	s_add_u32 s8, s8, s10
	s_addc_u32 s9, s9, s11
	s_add_u32 s8, s8, 0x4000
	s_addc_u32 s9, s9, 0
	s_mul_i32 s11, s9, 0x1600
	s_mul_hi_u32 s9, s8, 0x1600
	s_add_i32 s9, s9, s11
	s_mul_i32 s8, s8, 0x1600
	s_add_u32 s8, s52, s8
	s_addc_u32 s9, s53, s9
	s_add_i32 s11, s33, s6
	s_and_b32 s11, s11, 0x180
	s_lshl_b32 s11, s11, 1
	s_add_u32 s8, s8, s11
	s_addc_u32 s9, s9, 0
	s_add_u32 s8, s8, 0x1200
	s_addc_u32 s9, s9, 0
	v_lshlrev_b32_e32 v88, 1, v126
	v_mov_b32_e32 v89, v16
	v_lshl_add_u64 v[88:89], s[8:9], 0, v[88:89]
	global_load_dword v79, v[128:129], off
	global_load_dword v80, v[128:129], off offset:256
	global_load_ushort v81, v[88:89], off
	global_load_ushort v82, v[88:89], off offset:128
.Lch_pre2:
	v_lshl_add_u64 v[4:5], v[124:125], 0, s[2:3]
	global_store_dwordx4 v[4:5], v[8:11], off sc1
	global_store_dwordx4 v[4:5], v[12:15], off offset:512 sc1
	global_store_dwordx4 v[4:5], v[18:21], off offset:1024 sc1
	global_store_dwordx4 v[4:5], v[22:25], off offset:1536 sc1
	global_store_dwordx4 v[4:5], v[26:29], off offset:2048 sc1
	global_store_dwordx4 v[4:5], v[30:33], off offset:2560 sc1
	global_store_dwordx4 v[4:5], v[34:37], off offset:3072 sc1
	global_store_dwordx4 v[4:5], v[0:3], off offset:3584 sc1
	s_waitcnt lgkmcnt(0)
	s_barrier
	ds_read2st64_b32 v[0:1], v167 offset1:2
	ds_read2st64_b32 v[2:3], v167 offset0:4 offset1:6
	ds_read2st64_b32 v[4:5], v167 offset0:8 offset1:10
	v_readfirstlane_b32 s1, v17
	s_ashr_i32 s1, s1, 6
	s_waitcnt lgkmcnt(2)
	v_add_f32_e32 v0, 0, v0
	v_add_f32_e32 v0, v0, v1
	s_waitcnt lgkmcnt(1)
	v_add_f32_e32 v2, v0, v2
	ds_read2st64_b32 v[0:1], v167 offset0:12 offset1:14
	v_add_f32_e32 v2, v2, v3
	s_waitcnt lgkmcnt(1)
	v_add_f32_e32 v4, v2, v4
	ds_read2st64_b32 v[2:3], v167 offset0:16 offset1:18
	v_add_f32_e32 v4, v4, v5
	s_waitcnt lgkmcnt(1)
	v_add_f32_e32 v0, v4, v0
	v_add_f32_e32 v4, v0, v1
	ds_read2st64_b32 v[0:1], v167 offset0:20 offset1:22
	s_waitcnt lgkmcnt(1)
	v_add_f32_e32 v2, v4, v2
	ds_read2st64_b32 v[4:5], v167 offset0:24 offset1:26
	v_add_f32_e32 v6, v2, v3
	ds_read2st64_b32 v[2:3], v167 offset0:28 offset1:30
	s_waitcnt lgkmcnt(2)
	v_add_f32_e32 v0, v6, v0
	v_add_f32_e32 v0, v0, v1
	s_waitcnt lgkmcnt(1)
	v_add_f32_e32 v0, v0, v4
	v_add_f32_e32 v0, v0, v5
	s_waitcnt lgkmcnt(0)
	v_add_f32_e32 v0, v0, v2
	v_add_f32_e32 v0, v0, v3
	ds_write_b32 v164, v0 offset:8192
	s_waitcnt lgkmcnt(0)
	s_barrier
	s_cmp_gt_i32 s1, 3
	s_cbranch_scc1 .LBB0_1190
	v_lshl_add_u32 v0, s1, 9, v165
	ds_read2st64_b32 v[0:1], v0 offset0:32 offset1:33
	v_and_b32_e32 v3, 64, v221
	v_add_u32_e32 v3, 64, v3
	v_xor_b32_e32 v4, 1, v221
	v_cmp_lt_i32_e32 vcc, v4, v3
	s_waitcnt lgkmcnt(0)
	v_mul_f32_e32 v2, v1, v1
	v_fmac_f32_e32 v2, v0, v0
	v_cndmask_b32_e32 v4, v221, v4, vcc
	v_lshlrev_b32_e32 v4, 2, v4
	ds_bpermute_b32 v4, v4, v2
	s_and_b32 s0, s0, -4
	s_ashr_i32 s2, s0, 31
	s_ashr_i32 s3, s1, 31
	s_add_u32 s0, s0, s1
	s_waitcnt lgkmcnt(0)
	v_add_f32_e32 v2, v2, v4
	v_xor_b32_e32 v4, 2, v221
	v_cmp_lt_i32_e32 vcc, v4, v3
	s_addc_u32 s1, s2, s3
	s_add_u32 s0, s0, 0x4000
	v_cndmask_b32_e32 v4, v221, v4, vcc
	v_lshlrev_b32_e32 v4, 2, v4
	ds_bpermute_b32 v4, v4, v2
	s_addc_u32 s1, s1, 0
	s_mul_i32 s2, s1, 0x1600
	s_mul_hi_u32 s3, s0, 0x1600
	s_add_i32 s3, s3, s2
	s_waitcnt lgkmcnt(0)
	v_add_f32_e32 v2, v2, v4
	v_xor_b32_e32 v4, 4, v221
	v_cmp_lt_i32_e32 vcc, v4, v3
	s_mul_i32 s2, s0, 0x1600
	s_add_u32 s4, s52, s2
	v_cndmask_b32_e32 v4, v221, v4, vcc
	v_lshlrev_b32_e32 v4, 2, v4
	ds_bpermute_b32 v4, v4, v2
	s_addc_u32 s3, s53, s3
	s_add_i32 s2, s33, s6
	s_and_b32 s2, s2, 0x180
	s_lshl_b32 s2, s2, 1
	s_waitcnt lgkmcnt(0)
	v_add_f32_e32 v2, v2, v4
	v_xor_b32_e32 v4, 8, v221
	v_cmp_lt_i32_e32 vcc, v4, v3
	s_add_u32 s4, s4, s2
	s_addc_u32 s5, s3, 0
	v_cndmask_b32_e32 v4, v221, v4, vcc
	v_lshlrev_b32_e32 v4, 2, v4
	ds_bpermute_b32 v4, v4, v2
	s_lshl_b64 s[0:1], s[0:1], 11
	s_add_u32 s0, s14, s0
	s_addc_u32 s1, s15, s1
	s_add_u32 s0, s0, s2
	s_waitcnt lgkmcnt(0)
	v_add_f32_e32 v2, v2, v4
	v_xor_b32_e32 v4, 16, v221
	v_cmp_lt_i32_e32 vcc, v4, v3
	s_addc_u32 s1, s1, 0
	s_nop 0
	v_cndmask_b32_e32 v4, v221, v4, vcc
	v_lshlrev_b32_e32 v4, 2, v4
	ds_bpermute_b32 v4, v4, v2
	s_waitcnt lgkmcnt(0)
	v_add_f32_e32 v2, v2, v4
	v_xor_b32_e32 v4, 32, v221
	v_cmp_lt_i32_e32 vcc, v4, v3
	s_nop 1
	v_cndmask_b32_e32 v3, v221, v4, vcc
	v_lshlrev_b32_e32 v3, 2, v3
	ds_bpermute_b32 v3, v3, v2
	s_waitcnt lgkmcnt(0)
	v_add_f32_e32 v2, v2, v3
	v_fmamk_f32 v2, v2, 0x3c000000, v218
	v_rsq_f32_e32 v8, v2
	v_lshlrev_b32_e32 v10, 1, v126
	v_mul_f32_e32 v0, v0, v8
	v_mul_f32_e32 v1, v1, v8
	s_waitcnt vmcnt(8)
	v_mul_f32_e32 v0, v79, v0
	v_lshlrev_b32_e32 v81, 16, v81
	v_mul_f32_e32 v0, v0, v81
	v_cvt_pk_bf16_f32 v0, v0, v0
	global_store_short v10, v0, s[0:1] offset:1024
	v_mul_f32_e32 v1, v80, v1
	v_lshlrev_b32_e32 v82, 16, v82
	v_mul_f32_e32 v1, v1, v82
	v_cvt_pk_bf16_f32 v1, v1, v1
	global_store_short v10, v1, s[0:1] offset:1152
	s_branch .LBB0_1190
